# mixers: serialized ds_read->wait->MFMA strips in phases B and D batched (fragment reads issued up front into dead quads, counted lgkmcnt), on top of K-loop changes
# speedup vs baseline: 1.0092x; 1.0055x over previous
.LBB0_467:
	s_or_b64 exec, exec, s[2:3]
	s_ashr_i32 s2, s15, 2
	v_lshrrev_b32_e32 v5, 4, v101
	v_and_or_b32 v4, s2, -16, v0
	v_xor_b32_e32 v6, v0, v5
	v_lshl_add_u32 v46, v4, 8, 0
	v_lshl_add_u32 v47, v0, 8, 0
	v_lshlrev_b32_e32 v10, 4, v6
	v_add_u32_e32 v6, v46, v10
	v_add_u32_e32 v38, v47, v10
	ds_read_b128 v[6:9], v6 offset:32768
	ds_read_b128 v[10:13], v38
	ds_read_b128 v[14:17], v38 offset:4096
	ds_read_b128 v[18:21], v38 offset:8192
	ds_read_b128 v[22:25], v38 offset:12288
	ds_read_b128 v[26:29], v38 offset:16384
	ds_read_b128 v[30:33], v38 offset:20480
	ds_read_b128 v[34:37], v38 offset:24576
	ds_read_b128 v[38:41], v38 offset:28672
	s_waitcnt lgkmcnt(7)
	v_mfma_f32_16x16x32_bf16 v[10:13], v[10:13], v[6:9], 0
	v_lshlrev_b64 v[2:3], 15, v[2:3]
	v_lshl_add_u64 v[2:3], s[10:11], 0, v[2:3]
	s_waitcnt lgkmcnt(6)
	v_mfma_f32_16x16x32_bf16 v[14:17], v[14:17], v[6:9], 0
	s_waitcnt lgkmcnt(5)
	v_mfma_f32_16x16x32_bf16 v[18:21], v[18:21], v[6:9], 0
	s_waitcnt lgkmcnt(4)
	v_mfma_f32_16x16x32_bf16 v[22:25], v[22:25], v[6:9], 0
	s_waitcnt lgkmcnt(3)
	v_mfma_f32_16x16x32_bf16 v[26:29], v[26:29], v[6:9], 0
	s_waitcnt lgkmcnt(2)
	v_mfma_f32_16x16x32_bf16 v[30:33], v[30:33], v[6:9], 0
	s_waitcnt lgkmcnt(1)
	v_mfma_f32_16x16x32_bf16 v[34:37], v[34:37], v[6:9], 0
	s_waitcnt lgkmcnt(0)
	v_mfma_f32_16x16x32_bf16 v[6:9], v[38:41], v[6:9], 0
	v_bitop3_b32 v38, v0, v5, 4 bitop3:0x1e
	v_lshlrev_b32_e32 v42, 4, v38
	v_add_u32_e32 v38, v46, v42
	v_add_u32_e32 v48, v47, v42
	ds_read_b128 v[38:41], v38 offset:32768
	ds_read_b128 v[42:45], v48
	ds_read_b128 v[128:131], v48 offset:4096
	ds_read_b128 v[132:135], v48 offset:8192
	ds_read_b128 v[136:139], v48 offset:12288
	ds_read_b128 v[140:143], v48 offset:16384
	ds_read_b128 v[144:147], v48 offset:20480
	ds_read_b128 v[148:151], v48 offset:24576
	ds_read_b128 v[152:155], v48 offset:28672
	s_waitcnt lgkmcnt(7)
	v_mfma_f32_16x16x32_bf16 v[10:13], v[42:45], v[38:41], v[10:13]
	s_waitcnt lgkmcnt(6)
	v_mfma_f32_16x16x32_bf16 v[14:17], v[128:131], v[38:41], v[14:17]
	s_waitcnt lgkmcnt(5)
	v_mfma_f32_16x16x32_bf16 v[18:21], v[132:135], v[38:41], v[18:21]
	s_waitcnt lgkmcnt(4)
	v_mfma_f32_16x16x32_bf16 v[22:25], v[136:139], v[38:41], v[22:25]
	s_waitcnt lgkmcnt(3)
	v_mfma_f32_16x16x32_bf16 v[26:29], v[140:143], v[38:41], v[26:29]
	s_waitcnt lgkmcnt(2)
	v_mfma_f32_16x16x32_bf16 v[30:33], v[144:147], v[38:41], v[30:33]
	s_waitcnt lgkmcnt(1)
	v_mfma_f32_16x16x32_bf16 v[34:37], v[148:151], v[38:41], v[34:37]
	s_waitcnt lgkmcnt(0)
	v_mfma_f32_16x16x32_bf16 v[6:9], v[152:155], v[38:41], v[6:9]
	v_bitop3_b32 v38, v0, v5, 8 bitop3:0x1e
	v_lshlrev_b32_e32 v42, 4, v38
	v_add_u32_e32 v38, v46, v42
	v_add_u32_e32 v48, v47, v42
	ds_read_b128 v[38:41], v38 offset:32768
	ds_read_b128 v[42:45], v48
	ds_read_b128 v[128:131], v48 offset:4096
	ds_read_b128 v[132:135], v48 offset:8192
	ds_read_b128 v[136:139], v48 offset:12288
	ds_read_b128 v[140:143], v48 offset:16384
	ds_read_b128 v[144:147], v48 offset:20480
	ds_read_b128 v[148:151], v48 offset:24576
	ds_read_b128 v[152:155], v48 offset:28672
	s_waitcnt lgkmcnt(7)
	v_mfma_f32_16x16x32_bf16 v[10:13], v[42:45], v[38:41], v[10:13]
	v_bitop3_b32 v0, v0, v5, 12 bitop3:0x1e
	v_lshlrev_b32_e32 v0, 4, v0
	s_waitcnt lgkmcnt(6)
	v_mfma_f32_16x16x32_bf16 v[14:17], v[128:131], v[38:41], v[14:17]
	v_add_u32_e32 v5, v46, v0
	v_add_u32_e32 v0, v47, v0
	s_waitcnt lgkmcnt(5)
	v_mfma_f32_16x16x32_bf16 v[18:21], v[132:135], v[38:41], v[18:21]
	s_waitcnt lgkmcnt(4)
	v_mfma_f32_16x16x32_bf16 v[22:25], v[136:139], v[38:41], v[22:25]
	s_waitcnt lgkmcnt(3)
	v_mfma_f32_16x16x32_bf16 v[26:29], v[140:143], v[38:41], v[26:29]
	s_waitcnt lgkmcnt(2)
	v_mfma_f32_16x16x32_bf16 v[30:33], v[144:147], v[38:41], v[30:33]
	s_waitcnt lgkmcnt(1)
	v_mfma_f32_16x16x32_bf16 v[34:37], v[148:151], v[38:41], v[34:37]
	s_waitcnt lgkmcnt(0)
	v_mfma_f32_16x16x32_bf16 v[6:9], v[152:155], v[38:41], v[6:9]
	ds_read_b128 v[38:41], v5 offset:32768
	ds_read_b128 v[42:45], v0
	ds_read_b128 v[128:131], v0 offset:4096
	ds_read_b128 v[132:135], v0 offset:8192
	ds_read_b128 v[136:139], v0 offset:12288
	ds_read_b128 v[140:143], v0 offset:16384
	ds_read_b128 v[144:147], v0 offset:20480
	ds_read_b128 v[148:151], v0 offset:24576
	ds_read_b128 v[152:155], v0 offset:28672
	v_ashrrev_i32_e32 v5, 31, v4
	s_waitcnt lgkmcnt(7)
	v_mfma_f32_16x16x32_bf16 v[10:13], v[42:45], v[38:41], v[10:13]
	v_lshlrev_b64 v[4:5], 8, v[4:5]
	v_lshl_add_u64 v[2:3], v[2:3], 0, v[4:5]
	s_waitcnt lgkmcnt(6)
	v_mfma_f32_16x16x32_bf16 v[14:17], v[128:131], v[38:41], v[14:17]
	s_nop 1
	s_nop 1
	v_cvt_pk_bf16_f32 v10, v10, v11
	v_cvt_pk_bf16_f32 v11, v12, v13
	s_waitcnt lgkmcnt(5)
	v_mfma_f32_16x16x32_bf16 v[18:21], v[132:135], v[38:41], v[18:21]
	s_waitcnt lgkmcnt(4)
	v_mfma_f32_16x16x32_bf16 v[22:25], v[136:139], v[38:41], v[22:25]
	s_waitcnt lgkmcnt(3)
	v_mfma_f32_16x16x32_bf16 v[26:29], v[140:143], v[38:41], v[26:29]
	s_waitcnt lgkmcnt(2)
	v_mfma_f32_16x16x32_bf16 v[30:33], v[144:147], v[38:41], v[30:33]
	s_waitcnt lgkmcnt(1)
	v_mfma_f32_16x16x32_bf16 v[34:37], v[148:151], v[38:41], v[34:37]
	v_lshrrev_b32_e32 v0, 1, v98
	v_and_b32_e32 v0, 24, v0
	v_lshl_add_u64 v[2:3], v[2:3], 0, v[0:1]
	v_lshl_add_u64 v[4:5], v[2:3], 0, s[66:67]
	v_add_co_u32_e32 v2, vcc, s63, v2
	s_waitcnt lgkmcnt(0)
	v_mfma_f32_16x16x32_bf16 v[6:9], v[152:155], v[38:41], v[6:9]
	v_addc_co_u32_e32 v3, vcc, 0, v3, vcc
	global_store_dwordx2 v[2:3], v[10:11], off
	v_cvt_pk_bf16_f32 v2, v14, v15
	v_cvt_pk_bf16_f32 v3, v16, v17
	global_store_dwordx2 v[4:5], v[2:3], off offset:32
	v_cvt_pk_bf16_f32 v2, v18, v19
	v_cvt_pk_bf16_f32 v3, v20, v21
	global_store_dwordx2 v[4:5], v[2:3], off offset:64
	v_cvt_pk_bf16_f32 v2, v22, v23
	v_cvt_pk_bf16_f32 v3, v24, v25
	global_store_dwordx2 v[4:5], v[2:3], off offset:96
	v_cvt_pk_bf16_f32 v2, v26, v27
	v_cvt_pk_bf16_f32 v3, v28, v29
	global_store_dwordx2 v[4:5], v[2:3], off offset:128
	v_cvt_pk_bf16_f32 v2, v30, v31
	v_cvt_pk_bf16_f32 v3, v32, v33
	global_store_dwordx2 v[4:5], v[2:3], off offset:160
	v_cvt_pk_bf16_f32 v2, v34, v35
	v_cvt_pk_bf16_f32 v3, v36, v37
	global_store_dwordx2 v[4:5], v[2:3], off offset:192
	v_cvt_pk_bf16_f32 v2, v6, v7
	v_cvt_pk_bf16_f32 v3, v8, v9
	global_store_dwordx2 v[4:5], v[2:3], off offset:224
	s_barrier
	s_cmpk_lt_i32 s4, 0x400
	s_cbranch_scc1 .LBB0_452

.LBB0_470:
	v_xor_b32_e32 v32, v19, v0
	v_lshlrev_b32_e32 v36, 4, v32
	v_add_u32_e32 v32, v30, v36
	v_add_u32_e32 v40, v31, v36
	ds_read_b128 v[32:35], v32
	ds_read_b128 v[36:39], v40 offset:32768
	ds_read_b128 v[44:47], v40 offset:36864
	ds_read_b128 v[48:51], v40 offset:40960
	ds_read_b128 v[52:55], v40 offset:45056
	s_add_i32 s2, s2, -1
	v_add_u32_e32 v19, 4, v19
	s_cmp_lg_u32 s2, 0
	s_waitcnt lgkmcnt(3)
	v_mfma_f32_16x16x32_bf16 v[14:17], v[36:39], v[32:35], v[14:17]
	s_waitcnt lgkmcnt(2)
	v_mfma_f32_16x16x32_bf16 v[10:13], v[44:47], v[32:35], v[10:13]
	s_waitcnt lgkmcnt(1)
	v_mfma_f32_16x16x32_bf16 v[6:9], v[48:51], v[32:35], v[6:9]
	s_waitcnt lgkmcnt(0)
	v_mfma_f32_16x16x32_bf16 v[2:5], v[52:55], v[32:35], v[2:5]
	s_cbranch_scc1 .LBB0_470
	s_branch .LBB0_451

.LBB0_745:
	s_or_b64 exec, exec, s[2:3]
	s_cmp_lt_i32 s37, 7
	s_cselect_b64 s[2:3], -1, 0
	v_mul_f32_e32 v18, v18, v36
	s_cmp_lt_i32 s37, 6
	v_cndmask_b32_e64 v36, v18, 0, s[2:3]
	s_cselect_b64 s[4:5], -1, 0
	v_mul_f32_e32 v18, v32, v37
	v_cndmask_b32_e64 v37, v18, 0, s[4:5]
	v_mul_f32_e32 v18, v31, v74
	v_cndmask_b32_e64 v72, v18, 0, s[4:5]
	v_mul_f32_e32 v18, v30, v73
	v_mul_f32_e32 v20, v20, v101
	v_cndmask_b32_e64 v74, v18, 0, s[4:5]
	v_mul_f32_e32 v18, v33, v78
	s_cmp_lt_i32 s37, 5
	v_cndmask_b32_e64 v34, v20, 0, s[2:3]
	v_cndmask_b32_e64 v73, v18, 0, s[4:5]
	s_cselect_b64 s[4:5], -1, 0
	v_mul_f32_e32 v20, v28, v75
	v_cndmask_b32_e64 v75, v20, 0, s[4:5]
	v_mul_f32_e32 v20, v27, v76
	v_cndmask_b32_e64 v76, v20, 0, s[4:5]
	v_mul_f32_e32 v20, v26, v77
	v_cndmask_b32_e64 v78, v20, 0, s[4:5]
	v_mul_f32_e32 v20, v29, v82
	s_cmp_lt_i32 s37, 4
	v_cndmask_b32_e64 v77, v20, 0, s[4:5]
	s_cselect_b64 s[4:5], -1, 0
	v_mul_f32_e32 v20, v24, v79
	v_cndmask_b32_e64 v79, v20, 0, s[4:5]
	v_mul_f32_e32 v20, v23, v80
	v_cndmask_b32_e64 v80, v20, 0, s[4:5]
	v_mul_f32_e32 v20, v22, v81
	v_cndmask_b32_e64 v82, v20, 0, s[4:5]
	v_mul_f32_e32 v20, v25, v88
	s_cmp_lt_i32 s37, 3
	v_cndmask_b32_e64 v81, v20, 0, s[4:5]
	s_cselect_b64 s[4:5], -1, 0
	v_mul_f32_e32 v14, v14, v87
	v_mul_f32_e32 v16, v16, v85
	v_mul_f32_e32 v15, v15, v86
	v_cndmask_b32_e64 v88, v14, 0, s[4:5]
	v_mul_f32_e32 v14, v17, v92
	s_cmp_lt_i32 s37, 2
	v_cndmask_b32_e64 v85, v16, 0, s[4:5]
	v_cndmask_b32_e64 v86, v15, 0, s[4:5]
	v_cndmask_b32_e64 v87, v14, 0, s[4:5]
	s_cselect_b64 s[4:5], -1, 0
	v_mul_f32_e32 v10, v10, v91
	v_mul_f32_e32 v12, v12, v89
	v_mul_f32_e32 v11, v11, v90
	v_cndmask_b32_e64 v92, v10, 0, s[4:5]
	v_mul_f32_e32 v10, v13, v98
	s_cmp_lt_i32 s37, 1
	v_cndmask_b32_e64 v89, v12, 0, s[4:5]
	v_cndmask_b32_e64 v90, v11, 0, s[4:5]
	v_cndmask_b32_e64 v91, v10, 0, s[4:5]
	s_cselect_b64 s[4:5], -1, 0
	v_mul_f32_e32 v6, v6, v97
	v_mul_f32_e32 v8, v8, v95
	v_mul_f32_e32 v7, v7, v96
	v_cndmask_b32_e64 v98, v6, 0, s[4:5]
	v_mul_f32_e32 v6, v9, v99
	s_cmp_lt_i32 s37, 0
	v_cndmask_b32_e64 v95, v8, 0, s[4:5]
	v_cndmask_b32_e64 v96, v7, 0, s[4:5]
	v_cndmask_b32_e64 v97, v6, 0, s[4:5]
	s_cselect_b64 s[4:5], -1, 0
	v_mul_f32_e32 v2, v2, v83
	v_mul_f32_e32 v4, v4, v94
	v_mul_f32_e32 v3, v3, v84
	v_cndmask_b32_e64 v99, v2, 0, s[4:5]
	v_mul_f32_e32 v2, v5, v93
	v_lshrrev_b32_e32 v8, 5, v191
	v_and_b32_e32 v0, 8, v0
	v_cndmask_b32_e64 v94, v4, 0, s[4:5]
	v_cndmask_b32_e64 v84, v3, 0, s[4:5]
	v_cndmask_b32_e64 v93, v2, 0, s[4:5]
	v_add_u32_e32 v0, v62, v0
	v_xor_b32_e32 v9, v8, v60
	v_cvt_pk_bf16_f32 v2, v99, v84
	v_cvt_pk_bf16_f32 v3, v94, v93
	v_lshl_add_u32 v9, v9, 4, v0
	s_barrier
	ds_write_b64 v9, v[2:3] offset:32768
	v_bitop3_b32 v2, v8, v60, 2 bitop3:0x36
	v_cvt_pk_bf16_f32 v6, v98, v96
	v_cvt_pk_bf16_f32 v7, v95, v97
	v_lshl_add_u32 v2, v2, 4, v0
	ds_write_b64 v2, v[6:7] offset:32768
	v_bitop3_b32 v2, v8, v60, 4 bitop3:0x36
	v_cvt_pk_bf16_f32 v10, v92, v90
	v_cvt_pk_bf16_f32 v11, v89, v91
	v_lshl_add_u32 v2, v2, 4, v0
	ds_write_b64 v2, v[10:11] offset:32768
	v_bitop3_b32 v2, v8, v60, 6 bitop3:0x36
	v_cvt_pk_bf16_f32 v14, v88, v86
	v_cvt_pk_bf16_f32 v15, v85, v87
	v_lshl_add_u32 v2, v2, 4, v0
	ds_write_b64 v2, v[14:15] offset:32768
	v_bitop3_b32 v2, v8, v60, 8 bitop3:0x36
	v_cvt_pk_bf16_f32 v22, v82, v80
	v_cvt_pk_bf16_f32 v23, v79, v81
	v_lshl_add_u32 v2, v2, 4, v0
	ds_write_b64 v2, v[22:23] offset:32768
	v_bitop3_b32 v2, v8, v60, 10 bitop3:0x36
	v_cvt_pk_bf16_f32 v26, v78, v76
	v_cvt_pk_bf16_f32 v27, v75, v77
	v_lshl_add_u32 v2, v2, 4, v0
	v_mul_f32_e32 v19, v19, v35
	ds_write_b64 v2, v[26:27] offset:32768
	v_bitop3_b32 v2, v8, v60, 12 bitop3:0x36
	v_cndmask_b32_e64 v35, v19, 0, s[2:3]
	v_cvt_pk_bf16_f32 v18, v74, v72
	v_cvt_pk_bf16_f32 v19, v37, v73
	v_mul_f32_e32 v4, v21, v100
	v_lshl_add_u32 v2, v2, 4, v0
	v_cndmask_b32_e64 v83, v4, 0, s[2:3]
	ds_write_b64 v2, v[18:19] offset:32768
	v_bitop3_b32 v2, v8, v60, 14 bitop3:0x36
	v_cvt_pk_bf16_f32 v4, v36, v35
	v_cvt_pk_bf16_f32 v5, v34, v83
	v_lshl_add_u32 v0, v2, 4, v0
	ds_write_b64 v0, v[4:5] offset:32768
	v_add_u32_e32 v0, s36, v63
	v_add_u32_e32 v64, v0, v64
	ds_read_b128 v[6:9], v64
	ds_read_b128 v[10:13], v64 offset:4096
	ds_read_b128 v[14:17], v64 offset:8192
	ds_read_b128 v[18:21], v64 offset:12288
	ds_read_b128 v[22:25], v64 offset:16384
	ds_read_b128 v[26:29], v64 offset:20480
	ds_read_b128 v[30:33], v64 offset:24576
	ds_read_b128 v[100:103], v64 offset:28672
	ds_read_b128 v[2:5], v65
	v_add_u32_e32 v64, v0, v66
	ds_read_b128 v[104:107], v64
	s_waitcnt lgkmcnt(1)
	v_mfma_f32_16x16x32_bf16 v[6:9], v[6:9], v[2:5], 0
	s_or_b32 s2, s34, 15
	s_cmpk_lt_i32 s2, 0xffe1
	v_mfma_f32_16x16x32_bf16 v[10:13], v[10:13], v[2:5], 0
	v_mfma_f32_16x16x32_bf16 v[14:17], v[14:17], v[2:5], 0
	v_mfma_f32_16x16x32_bf16 v[18:21], v[18:21], v[2:5], 0
	v_mfma_f32_16x16x32_bf16 v[22:25], v[22:25], v[2:5], 0
	v_mfma_f32_16x16x32_bf16 v[26:29], v[26:29], v[2:5], 0
	v_mfma_f32_16x16x32_bf16 v[30:33], v[30:33], v[2:5], 0
	v_mfma_f32_16x16x32_bf16 v[2:5], v[100:103], v[2:5], 0
	ds_read_b128 v[100:103], v70
	s_waitcnt lgkmcnt(0)
	v_mfma_f32_16x16x32_bf16 v[6:9], v[104:107], v[100:103], v[6:9]
	ds_read_b128 v[104:107], v64 offset:4096
	ds_read_b128 v[120:123], v64 offset:8192
	ds_read_b128 v[124:127], v64 offset:12288
	ds_read_b128 v[128:131], v64 offset:16384
	ds_read_b128 v[132:135], v64 offset:20480
	ds_read_b128 v[136:139], v64 offset:24576
	ds_read_b128 v[140:143], v64 offset:28672
	s_waitcnt lgkmcnt(6)
	v_mfma_f32_16x16x32_bf16 v[10:13], v[104:107], v[100:103], v[10:13]
	s_waitcnt lgkmcnt(5)
	v_mfma_f32_16x16x32_bf16 v[14:17], v[120:123], v[100:103], v[14:17]
	s_waitcnt lgkmcnt(4)
	v_mfma_f32_16x16x32_bf16 v[18:21], v[124:127], v[100:103], v[18:21]
	s_waitcnt lgkmcnt(3)
	v_mfma_f32_16x16x32_bf16 v[22:25], v[128:131], v[100:103], v[22:25]
	s_waitcnt lgkmcnt(2)
	v_mfma_f32_16x16x32_bf16 v[26:29], v[132:135], v[100:103], v[26:29]
	s_waitcnt lgkmcnt(1)
	v_mfma_f32_16x16x32_bf16 v[30:33], v[136:139], v[100:103], v[30:33]
	v_add_u32_e32 v64, v0, v68
	v_add_u32_e32 v0, v0, v67
	s_waitcnt lgkmcnt(0)
	v_mfma_f32_16x16x32_bf16 v[2:5], v[140:143], v[100:103], v[2:5]
	ds_read_b128 v[100:103], v69
	ds_read_b128 v[104:107], v64
	ds_read_b128 v[68:71], v71
	s_waitcnt lgkmcnt(1)
	v_mfma_f32_16x16x32_bf16 v[6:9], v[104:107], v[100:103], v[6:9]
	ds_read_b128 v[104:107], v64 offset:4096
	ds_read_b128 v[120:123], v64 offset:8192
	ds_read_b128 v[124:127], v64 offset:12288
	ds_read_b128 v[128:131], v64 offset:16384
	ds_read_b128 v[132:135], v64 offset:20480
	ds_read_b128 v[136:139], v64 offset:24576
	s_waitcnt lgkmcnt(5)
	v_mfma_f32_16x16x32_bf16 v[10:13], v[104:107], v[100:103], v[10:13]
	s_waitcnt lgkmcnt(4)
	v_mfma_f32_16x16x32_bf16 v[14:17], v[120:123], v[100:103], v[14:17]
	s_waitcnt lgkmcnt(3)
	v_mfma_f32_16x16x32_bf16 v[18:21], v[124:127], v[100:103], v[18:21]
	s_waitcnt lgkmcnt(2)
	v_mfma_f32_16x16x32_bf16 v[22:25], v[128:131], v[100:103], v[22:25]
	s_waitcnt lgkmcnt(1)
	v_mfma_f32_16x16x32_bf16 v[26:29], v[132:135], v[100:103], v[26:29]
	s_waitcnt lgkmcnt(0)
	v_mfma_f32_16x16x32_bf16 v[30:33], v[136:139], v[100:103], v[30:33]
	ds_read_b128 v[104:107], v64 offset:28672
	ds_read_b128 v[64:67], v0
	ds_read_b128 v[120:123], v0 offset:4096
	ds_read_b128 v[124:127], v0 offset:8192
	ds_read_b128 v[128:131], v0 offset:12288
	ds_read_b128 v[132:135], v0 offset:16384
	s_waitcnt lgkmcnt(4)
	v_mfma_f32_16x16x32_bf16 v[6:9], v[64:67], v[68:71], v[6:9]
	s_waitcnt lgkmcnt(3)
	v_mfma_f32_16x16x32_bf16 v[10:13], v[120:123], v[68:71], v[10:13]
	s_waitcnt lgkmcnt(2)
	v_mfma_f32_16x16x32_bf16 v[14:17], v[124:127], v[68:71], v[14:17]
	s_waitcnt lgkmcnt(1)
	v_mfma_f32_16x16x32_bf16 v[18:21], v[128:131], v[68:71], v[18:21]
	s_waitcnt lgkmcnt(0)
	v_mfma_f32_16x16x32_bf16 v[64:67], v[132:135], v[68:71], v[22:25]
	s_nop 2
	ds_read_b128 v[22:25], v0 offset:20480
	v_mfma_f32_16x16x32_bf16 v[2:5], v[104:107], v[100:103], v[2:5]
	s_waitcnt lgkmcnt(0)
	v_mfma_f32_16x16x32_bf16 v[100:103], v[22:25], v[68:71], v[26:29]
	ds_read_b128 v[22:25], v0 offset:24576
	s_waitcnt lgkmcnt(0)
	v_mfma_f32_16x16x32_bf16 v[104:107], v[22:25], v[68:71], v[30:33]
	ds_read_b128 v[22:25], v0 offset:28672
	v_sub_f32_e32 v0, v190, v59
	v_mul_f32_e32 v0, 0x3fb8aa3b, v0
	s_waitcnt lgkmcnt(0)
	v_mfma_f32_16x16x32_bf16 v[68:71], v[22:25], v[68:71], v[2:5]
	v_exp_f32_e32 v0, v0
	s_waitcnt lgkmcnt(0)
	s_nop 1
	v_pk_mul_f32 v[4:5], v[0:1], v[8:9] op_sel_hi:[0,1]
	v_pk_mul_f32 v[2:3], v[0:1], v[6:7] op_sel_hi:[0,1]
	v_pk_mul_f32 v[32:33], v[0:1], v[12:13] op_sel_hi:[0,1]
	v_pk_mul_f32 v[30:31], v[0:1], v[10:11] op_sel_hi:[0,1]
	v_pk_mul_f32 v[28:29], v[0:1], v[16:17] op_sel_hi:[0,1]
	v_pk_mul_f32 v[26:27], v[0:1], v[14:15] op_sel_hi:[0,1]
	v_pk_mul_f32 v[24:25], v[0:1], v[20:21] op_sel_hi:[0,1]
	v_pk_mul_f32 v[22:23], v[0:1], v[18:19] op_sel_hi:[0,1]
	v_pk_mul_f32 v[20:21], v[0:1], v[66:67] op_sel_hi:[0,1]
	v_pk_mul_f32 v[18:19], v[0:1], v[64:65] op_sel_hi:[0,1]
	v_pk_mul_f32 v[16:17], v[0:1], v[102:103] op_sel_hi:[0,1]
	v_pk_mul_f32 v[14:15], v[0:1], v[100:101] op_sel_hi:[0,1]
	v_pk_mul_f32 v[12:13], v[0:1], v[106:107] op_sel_hi:[0,1]
	v_pk_mul_f32 v[10:11], v[0:1], v[104:105] op_sel_hi:[0,1]
	v_pk_mul_f32 v[8:9], v[0:1], v[70:71] op_sel_hi:[0,1]
	v_pk_mul_f32 v[6:7], v[0:1], v[68:69] op_sel_hi:[0,1]
	s_cbranch_scc1 .LBB0_618
	s_ashr_i32 s3, s2, 31
	s_lshr_b32 s3, s3, 27
	s_add_i32 s2, s2, s3
	s_ashr_i32 s2, s2, 5
	v_add_u32_e32 v63, s23, v63
	s_add_i32 s2, s2, 1
.LBB0_747:
	v_xor_b32_e32 v64, v61, v60
	v_lshlrev_b32_e32 v68, 4, v64
	v_add_u32_e32 v64, v62, v68
	v_add_u32_e32 v100, v63, v68
	ds_read_b128 v[64:67], v64 offset:32768
	ds_read_b128 v[68:71], v100
	ds_read_b128 v[120:123], v100 offset:4096
	ds_read_b128 v[124:127], v100 offset:8192
	ds_read_b128 v[128:131], v100 offset:12288
	ds_read_b128 v[132:135], v100 offset:16384
	ds_read_b128 v[136:139], v100 offset:20480
	ds_read_b128 v[140:143], v100 offset:24576
	ds_read_b128 v[144:147], v100 offset:28672
	s_add_i32 s2, s2, -1
	v_add_u32_e32 v61, 4, v61
	s_cmp_lg_u32 s2, 0
	s_waitcnt lgkmcnt(7)
	v_mfma_f32_16x16x32_bf16 v[2:5], v[68:71], v[64:67], v[2:5]
	s_waitcnt lgkmcnt(6)
	v_mfma_f32_16x16x32_bf16 v[30:33], v[120:123], v[64:67], v[30:33]
	s_waitcnt lgkmcnt(5)
	v_mfma_f32_16x16x32_bf16 v[26:29], v[124:127], v[64:67], v[26:29]
	s_waitcnt lgkmcnt(4)
	v_mfma_f32_16x16x32_bf16 v[22:25], v[128:131], v[64:67], v[22:25]
	s_waitcnt lgkmcnt(3)
	v_mfma_f32_16x16x32_bf16 v[18:21], v[132:135], v[64:67], v[18:21]
	s_waitcnt lgkmcnt(2)
	v_mfma_f32_16x16x32_bf16 v[14:17], v[136:139], v[64:67], v[14:17]
	s_waitcnt lgkmcnt(1)
	v_mfma_f32_16x16x32_bf16 v[10:13], v[140:143], v[64:67], v[10:13]
	s_waitcnt lgkmcnt(0)
	v_mfma_f32_16x16x32_bf16 v[6:9], v[144:147], v[64:67], v[6:9]
	s_cbranch_scc1 .LBB0_747
	s_branch .LBB0_618
